# attention QK^T stage rescheduled with K fragments read ahead; filter MLP weight loads issued in bulk and output layer software-pipelined
# speedup vs baseline: 1.0497x; 1.0070x over previous
.LBB0_59:
	s_or_b64 exec, exec, s[22:23]
	ds_write_b32 v64, v28
	s_waitcnt lgkmcnt(0)
	s_barrier
	global_load_dword v4, v[12:13], off
	s_mov_b32 s16, 0
	v_mov_b64_e32 v[28:29], v[20:21]
	s_mov_b64 s[98:99], 0x1000
	global_load_dword v140, v[28:29], off offset:-512
	global_load_dword v141, v[28:29], off offset:-256
	global_load_dword v142, v[28:29], off
	global_load_dword v143, v[28:29], off offset:256
	global_load_dword v144, v[28:29], off offset:512
	global_load_dword v145, v[28:29], off offset:768
	global_load_dword v146, v[28:29], off offset:1024
	global_load_dword v147, v[28:29], off offset:1280
	global_load_dword v148, v[28:29], off offset:1536
	global_load_dword v149, v[28:29], off offset:1792
	global_load_dword v150, v[28:29], off offset:2048
	global_load_dword v151, v[28:29], off offset:2304
	global_load_dword v152, v[28:29], off offset:2560
	global_load_dword v153, v[28:29], off offset:2816
	global_load_dword v154, v[28:29], off offset:3072
	global_load_dword v155, v[28:29], off offset:3328
	v_lshl_add_u64 v[28:29], v[28:29], 0, s[98:99]
	global_load_dword v156, v[28:29], off offset:-512
	global_load_dword v157, v[28:29], off offset:-256
	global_load_dword v158, v[28:29], off
	global_load_dword v159, v[28:29], off offset:256
	global_load_dword v160, v[28:29], off offset:512
	global_load_dword v161, v[28:29], off offset:768
	global_load_dword v162, v[28:29], off offset:1024
	global_load_dword v163, v[28:29], off offset:1280
	global_load_dword v164, v[28:29], off offset:1536
	global_load_dword v165, v[28:29], off offset:1792
	global_load_dword v166, v[28:29], off offset:2048
	global_load_dword v167, v[28:29], off offset:2304
	global_load_dword v168, v[28:29], off offset:2560
	global_load_dword v169, v[28:29], off offset:2816
	global_load_dword v170, v[28:29], off offset:3072
	global_load_dword v171, v[28:29], off offset:3328
	v_lshl_add_u64 v[28:29], v[28:29], 0, s[98:99]
	global_load_dword v173, v[28:29], off offset:-512
	global_load_dword v174, v[28:29], off offset:-256
	global_load_dword v175, v[28:29], off
	global_load_dword v176, v[28:29], off offset:256
	global_load_dword v177, v[28:29], off offset:512
	global_load_dword v178, v[28:29], off offset:768
	global_load_dword v179, v[28:29], off offset:1024
	global_load_dword v180, v[28:29], off offset:1280
	global_load_dword v181, v[28:29], off offset:1536
	global_load_dword v182, v[28:29], off offset:1792
	global_load_dword v183, v[28:29], off offset:2048
	global_load_dword v184, v[28:29], off offset:2304
	global_load_dword v185, v[28:29], off offset:2560
	global_load_dword v186, v[28:29], off offset:2816
	global_load_dword v187, v[28:29], off offset:3072
	global_load_dword v188, v[28:29], off offset:3328
	ds_read_b128 v[30:33], v65
	ds_read_b128 v[34:37], v65 offset:16
	ds_read_b128 v[38:41], v65 offset:32
	ds_read_b128 v[46:49], v65 offset:48
	s_waitcnt vmcnt(32) lgkmcnt(0)
	v_fmac_f32_e32 v4, v30, v140
	v_fmac_f32_e32 v4, v31, v141
	v_fmac_f32_e32 v4, v32, v142
	v_fmac_f32_e32 v4, v33, v143
	v_fmac_f32_e32 v4, v34, v144
	v_fmac_f32_e32 v4, v35, v145
	v_fmac_f32_e32 v4, v36, v146
	v_fmac_f32_e32 v4, v37, v147
	v_fmac_f32_e32 v4, v38, v148
	v_fmac_f32_e32 v4, v39, v149
	v_fmac_f32_e32 v4, v40, v150
	v_fmac_f32_e32 v4, v41, v151
	v_fmac_f32_e32 v4, v46, v152
	v_fmac_f32_e32 v4, v47, v153
	v_fmac_f32_e32 v4, v48, v154
	v_fmac_f32_e32 v4, v49, v155
	ds_read_b128 v[30:33], v65 offset:64
	ds_read_b128 v[34:37], v65 offset:80
	ds_read_b128 v[38:41], v65 offset:96
	ds_read_b128 v[46:49], v65 offset:112
	s_waitcnt vmcnt(16) lgkmcnt(0)
	v_fmac_f32_e32 v4, v30, v156
	v_fmac_f32_e32 v4, v31, v157
	v_fmac_f32_e32 v4, v32, v158
	v_fmac_f32_e32 v4, v33, v159
	v_fmac_f32_e32 v4, v34, v160
	v_fmac_f32_e32 v4, v35, v161
	v_fmac_f32_e32 v4, v36, v162
	v_fmac_f32_e32 v4, v37, v163
	v_fmac_f32_e32 v4, v38, v164
	v_fmac_f32_e32 v4, v39, v165
	v_fmac_f32_e32 v4, v40, v166
	v_fmac_f32_e32 v4, v41, v167
	v_fmac_f32_e32 v4, v46, v168
	v_fmac_f32_e32 v4, v47, v169
	v_fmac_f32_e32 v4, v48, v170
	v_fmac_f32_e32 v4, v49, v171
	v_lshl_add_u64 v[28:29], v[28:29], 0, s[98:99]
	global_load_dword v140, v[28:29], off offset:-512
	global_load_dword v141, v[28:29], off offset:-256
	global_load_dword v142, v[28:29], off
	global_load_dword v143, v[28:29], off offset:256
	global_load_dword v144, v[28:29], off offset:512
	global_load_dword v145, v[28:29], off offset:768
	global_load_dword v146, v[28:29], off offset:1024
	global_load_dword v147, v[28:29], off offset:1280
	global_load_dword v148, v[28:29], off offset:1536
	global_load_dword v149, v[28:29], off offset:1792
	global_load_dword v150, v[28:29], off offset:2048
	global_load_dword v151, v[28:29], off offset:2304
	global_load_dword v152, v[28:29], off offset:2560
	global_load_dword v153, v[28:29], off offset:2816
	global_load_dword v154, v[28:29], off offset:3072
	global_load_dword v155, v[28:29], off offset:3328
	ds_read_b128 v[30:33], v65 offset:128
	ds_read_b128 v[34:37], v65 offset:144
	ds_read_b128 v[38:41], v65 offset:160
	ds_read_b128 v[46:49], v65 offset:176
	s_waitcnt vmcnt(16) lgkmcnt(0)
	v_fmac_f32_e32 v4, v30, v173
	v_fmac_f32_e32 v4, v31, v174
	v_fmac_f32_e32 v4, v32, v175
	v_fmac_f32_e32 v4, v33, v176
	v_fmac_f32_e32 v4, v34, v177
	v_fmac_f32_e32 v4, v35, v178
	v_fmac_f32_e32 v4, v36, v179
	v_fmac_f32_e32 v4, v37, v180
	v_fmac_f32_e32 v4, v38, v181
	v_fmac_f32_e32 v4, v39, v182
	v_fmac_f32_e32 v4, v40, v183
	v_fmac_f32_e32 v4, v41, v184
	v_fmac_f32_e32 v4, v46, v185
	v_fmac_f32_e32 v4, v47, v186
	v_fmac_f32_e32 v4, v48, v187
	v_fmac_f32_e32 v4, v49, v188
	ds_read_b128 v[30:33], v65 offset:192
	ds_read_b128 v[34:37], v65 offset:208
	ds_read_b128 v[38:41], v65 offset:224
	ds_read_b128 v[46:49], v65 offset:240
	s_waitcnt vmcnt(0) lgkmcnt(0)
	v_fmac_f32_e32 v4, v30, v140
	v_fmac_f32_e32 v4, v31, v141
	v_fmac_f32_e32 v4, v32, v142
	v_fmac_f32_e32 v4, v33, v143
	v_fmac_f32_e32 v4, v34, v144
	v_fmac_f32_e32 v4, v35, v145
	v_fmac_f32_e32 v4, v36, v146
	v_fmac_f32_e32 v4, v37, v147
	v_fmac_f32_e32 v4, v38, v148
	v_fmac_f32_e32 v4, v39, v149
	v_fmac_f32_e32 v4, v40, v150
	v_fmac_f32_e32 v4, v41, v151
	v_fmac_f32_e32 v4, v46, v152
	v_fmac_f32_e32 v4, v47, v153
	v_fmac_f32_e32 v4, v48, v154
	v_fmac_f32_e32 v4, v49, v155
	v_mul_f32_e32 v28, v44, v4
	v_mul_f32_e32 v4, 0x3f22f983, v28
	v_rndne_f32_e32 v4, v4
	v_fmac_f32_e32 v28, 0xbfc90000, v4
	v_fmac_f32_e32 v28, 0xb9fda000, v4
	v_fmac_f32_e32 v28, 0xb3a22169, v4
	v_cvt_i32_f32_e32 v27, v4
	v_mul_f32_e32 v4, v28, v28
	v_fmamk_f32 v30, v4, 0xb94ca1f9, v24
	v_mul_f32_e32 v29, v28, v4
	v_fmaak_f32 v30, v4, v30, 0xbe2aaaa3
	v_fmac_f32_e32 v28, v29, v30
	v_and_b32_e32 v29, 3, v27
	v_cmp_ne_u32_e32 vcc, 0, v29
	s_and_saveexec_b64 s[22:23], vcc
	s_cbranch_execz .LBB0_63
	v_fmamk_f32 v27, v4, 0x37ccf5ce, v1
	v_pk_mul_f32 v[30:31], v[4:5], v[26:27] op_sel_hi:[0,1]
	v_mul_f32_e32 v32, v4, v4
	v_add_f32_e32 v4, 0x3d2aaaa5, v31
	v_sub_f32_e32 v27, 1.0, v30
	v_fmac_f32_e32 v27, v32, v4
	v_cmp_eq_u32_e32 vcc, 2, v29
	s_nop 1
	v_cndmask_b32_e32 v4, v27, v28, vcc
	v_cmp_eq_u32_e32 vcc, 1, v29
	s_nop 1
	v_cndmask_b32_e64 v28, -v4, v27, vcc
.LBB0_63:
	s_or_b64 exec, exec, s[22:23]
	ds_write_b32 v64, v28 offset:2048
	s_waitcnt lgkmcnt(0)
	s_barrier
	global_load_dword v4, v[14:15], off
	s_mov_b32 s16, 0
	v_mov_b64_e32 v[28:29], v[22:23]
	s_mov_b64 s[98:99], 0x1000
	global_load_dword v140, v[28:29], off offset:-512
	global_load_dword v141, v[28:29], off offset:-256
	global_load_dword v142, v[28:29], off
	global_load_dword v143, v[28:29], off offset:256
	global_load_dword v144, v[28:29], off offset:512
	global_load_dword v145, v[28:29], off offset:768
	global_load_dword v146, v[28:29], off offset:1024
	global_load_dword v147, v[28:29], off offset:1280
	global_load_dword v148, v[28:29], off offset:1536
	global_load_dword v149, v[28:29], off offset:1792
	global_load_dword v150, v[28:29], off offset:2048
	global_load_dword v151, v[28:29], off offset:2304
	global_load_dword v152, v[28:29], off offset:2560
	global_load_dword v153, v[28:29], off offset:2816
	global_load_dword v154, v[28:29], off offset:3072
	global_load_dword v155, v[28:29], off offset:3328
	v_lshl_add_u64 v[28:29], v[28:29], 0, s[98:99]
	global_load_dword v156, v[28:29], off offset:-512
	global_load_dword v157, v[28:29], off offset:-256
	global_load_dword v158, v[28:29], off
	global_load_dword v159, v[28:29], off offset:256
	global_load_dword v160, v[28:29], off offset:512
	global_load_dword v161, v[28:29], off offset:768
	global_load_dword v162, v[28:29], off offset:1024
	global_load_dword v163, v[28:29], off offset:1280
	global_load_dword v164, v[28:29], off offset:1536
	global_load_dword v165, v[28:29], off offset:1792
	global_load_dword v166, v[28:29], off offset:2048
	global_load_dword v167, v[28:29], off offset:2304
	global_load_dword v168, v[28:29], off offset:2560
	global_load_dword v169, v[28:29], off offset:2816
	global_load_dword v170, v[28:29], off offset:3072
	global_load_dword v171, v[28:29], off offset:3328
	v_lshl_add_u64 v[28:29], v[28:29], 0, s[98:99]
	global_load_dword v173, v[28:29], off offset:-512
	global_load_dword v174, v[28:29], off offset:-256
	global_load_dword v175, v[28:29], off
	global_load_dword v176, v[28:29], off offset:256
	global_load_dword v177, v[28:29], off offset:512
	global_load_dword v178, v[28:29], off offset:768
	global_load_dword v179, v[28:29], off offset:1024
	global_load_dword v180, v[28:29], off offset:1280
	global_load_dword v181, v[28:29], off offset:1536
	global_load_dword v182, v[28:29], off offset:1792
	global_load_dword v183, v[28:29], off offset:2048
	global_load_dword v184, v[28:29], off offset:2304
	global_load_dword v185, v[28:29], off offset:2560
	global_load_dword v186, v[28:29], off offset:2816
	global_load_dword v187, v[28:29], off offset:3072
	global_load_dword v188, v[28:29], off offset:3328
	ds_read_b128 v[30:33], v74
	ds_read_b128 v[34:37], v74 offset:16
	ds_read_b128 v[38:41], v74 offset:32
	ds_read_b128 v[46:49], v74 offset:48
	s_waitcnt vmcnt(32) lgkmcnt(0)
	v_fmac_f32_e32 v4, v30, v140
	v_fmac_f32_e32 v4, v31, v141
	v_fmac_f32_e32 v4, v32, v142
	v_fmac_f32_e32 v4, v33, v143
	v_fmac_f32_e32 v4, v34, v144
	v_fmac_f32_e32 v4, v35, v145
	v_fmac_f32_e32 v4, v36, v146
	v_fmac_f32_e32 v4, v37, v147
	v_fmac_f32_e32 v4, v38, v148
	v_fmac_f32_e32 v4, v39, v149
	v_fmac_f32_e32 v4, v40, v150
	v_fmac_f32_e32 v4, v41, v151
	v_fmac_f32_e32 v4, v46, v152
	v_fmac_f32_e32 v4, v47, v153
	v_fmac_f32_e32 v4, v48, v154
	v_fmac_f32_e32 v4, v49, v155
	ds_read_b128 v[30:33], v74 offset:64
	ds_read_b128 v[34:37], v74 offset:80
	ds_read_b128 v[38:41], v74 offset:96
	ds_read_b128 v[46:49], v74 offset:112
	s_waitcnt vmcnt(16) lgkmcnt(0)
	v_fmac_f32_e32 v4, v30, v156
	v_fmac_f32_e32 v4, v31, v157
	v_fmac_f32_e32 v4, v32, v158
	v_fmac_f32_e32 v4, v33, v159
	v_fmac_f32_e32 v4, v34, v160
	v_fmac_f32_e32 v4, v35, v161
	v_fmac_f32_e32 v4, v36, v162
	v_fmac_f32_e32 v4, v37, v163
	v_fmac_f32_e32 v4, v38, v164
	v_fmac_f32_e32 v4, v39, v165
	v_fmac_f32_e32 v4, v40, v166
	v_fmac_f32_e32 v4, v41, v167
	v_fmac_f32_e32 v4, v46, v168
	v_fmac_f32_e32 v4, v47, v169
	v_fmac_f32_e32 v4, v48, v170
	v_fmac_f32_e32 v4, v49, v171
	v_lshl_add_u64 v[28:29], v[28:29], 0, s[98:99]
	global_load_dword v140, v[28:29], off offset:-512
	global_load_dword v141, v[28:29], off offset:-256
	global_load_dword v142, v[28:29], off
	global_load_dword v143, v[28:29], off offset:256
	global_load_dword v144, v[28:29], off offset:512
	global_load_dword v145, v[28:29], off offset:768
	global_load_dword v146, v[28:29], off offset:1024
	global_load_dword v147, v[28:29], off offset:1280
	global_load_dword v148, v[28:29], off offset:1536
	global_load_dword v149, v[28:29], off offset:1792
	global_load_dword v150, v[28:29], off offset:2048
	global_load_dword v151, v[28:29], off offset:2304
	global_load_dword v152, v[28:29], off offset:2560
	global_load_dword v153, v[28:29], off offset:2816
	global_load_dword v154, v[28:29], off offset:3072
	global_load_dword v155, v[28:29], off offset:3328
	ds_read_b128 v[30:33], v74 offset:128
	ds_read_b128 v[34:37], v74 offset:144
	ds_read_b128 v[38:41], v74 offset:160
	ds_read_b128 v[46:49], v74 offset:176
	s_waitcnt vmcnt(16) lgkmcnt(0)
	v_fmac_f32_e32 v4, v30, v173
	v_fmac_f32_e32 v4, v31, v174
	v_fmac_f32_e32 v4, v32, v175
	v_fmac_f32_e32 v4, v33, v176
	v_fmac_f32_e32 v4, v34, v177
	v_fmac_f32_e32 v4, v35, v178
	v_fmac_f32_e32 v4, v36, v179
	v_fmac_f32_e32 v4, v37, v180
	v_fmac_f32_e32 v4, v38, v181
	v_fmac_f32_e32 v4, v39, v182
	v_fmac_f32_e32 v4, v40, v183
	v_fmac_f32_e32 v4, v41, v184
	v_fmac_f32_e32 v4, v46, v185
	v_fmac_f32_e32 v4, v47, v186
	v_fmac_f32_e32 v4, v48, v187
	v_fmac_f32_e32 v4, v49, v188
	ds_read_b128 v[30:33], v74 offset:192
	ds_read_b128 v[34:37], v74 offset:208
	ds_read_b128 v[38:41], v74 offset:224
	ds_read_b128 v[46:49], v74 offset:240
	s_waitcnt vmcnt(0) lgkmcnt(0)
	v_fmac_f32_e32 v4, v30, v140
	v_fmac_f32_e32 v4, v31, v141
	v_fmac_f32_e32 v4, v32, v142
	v_fmac_f32_e32 v4, v33, v143
	v_fmac_f32_e32 v4, v34, v144
	v_fmac_f32_e32 v4, v35, v145
	v_fmac_f32_e32 v4, v36, v146
	v_fmac_f32_e32 v4, v37, v147
	v_fmac_f32_e32 v4, v38, v148
	v_fmac_f32_e32 v4, v39, v149
	v_fmac_f32_e32 v4, v40, v150
	v_fmac_f32_e32 v4, v41, v151
	v_fmac_f32_e32 v4, v46, v152
	v_fmac_f32_e32 v4, v47, v153
	v_fmac_f32_e32 v4, v48, v154
	v_fmac_f32_e32 v4, v49, v155
	v_mul_f32_e32 v28, v44, v4
	v_mul_f32_e32 v4, 0x3f22f983, v28
	v_rndne_f32_e32 v4, v4
	v_fmac_f32_e32 v28, 0xbfc90000, v4
	v_fmac_f32_e32 v28, 0xb9fda000, v4
	v_fmac_f32_e32 v28, 0xb3a22169, v4
	v_cvt_i32_f32_e32 v27, v4
	v_mul_f32_e32 v4, v28, v28
	v_fmamk_f32 v30, v4, 0xb94ca1f9, v24
	v_mul_f32_e32 v29, v28, v4
	v_fmaak_f32 v30, v4, v30, 0xbe2aaaa3
	v_fmac_f32_e32 v28, v29, v30
	v_and_b32_e32 v29, 3, v27
	v_cmp_ne_u32_e32 vcc, 0, v29
	s_and_saveexec_b64 s[22:23], vcc
	s_cbranch_execz .LBB0_67
	v_fmamk_f32 v27, v4, 0x37ccf5ce, v1
	v_pk_mul_f32 v[30:31], v[4:5], v[26:27] op_sel_hi:[0,1]
	v_mul_f32_e32 v32, v4, v4
	v_add_f32_e32 v4, 0x3d2aaaa5, v31
	v_sub_f32_e32 v27, 1.0, v30
	v_fmac_f32_e32 v27, v32, v4
	v_cmp_eq_u32_e32 vcc, 2, v29
	s_nop 1
	v_cndmask_b32_e32 v4, v27, v28, vcc
	v_cmp_eq_u32_e32 vcc, 1, v29
	s_nop 1
	v_cndmask_b32_e64 v28, -v4, v27, vcc
.LBB0_67:
	s_or_b64 exec, exec, s[22:23]
	ds_write_b32 v64, v28
	v_mov_b32_e32 v28, 0
	s_mov_b32 s16, 0
	v_mov_b64_e32 v[44:45], v[16:17]
	v_mov_b32_e32 v29, v28
	v_mov_b64_e32 v[30:31], 0
	v_mov_b64_e32 v[34:35], 0
	v_mov_b64_e32 v[32:33], 0
	v_mov_b64_e32 v[36:37], 0
	v_mov_b64_e32 v[38:39], 0
	v_mov_b64_e32 v[42:43], 0
	v_mov_b64_e32 v[40:41], 0
	v_mov_b64_e32 v[46:47], 0
	v_mov_b64_e32 v[48:49], 0
	v_mov_b64_e32 v[52:53], 0
	v_mov_b64_e32 v[50:51], 0
	v_mov_b64_e32 v[54:55], 0
	v_mov_b64_e32 v[56:57], 0
	v_mov_b64_e32 v[60:61], 0
	v_mov_b64_e32 v[58:59], 0
	s_waitcnt lgkmcnt(0)
	s_barrier
	v_add_co_u32_e32 v80, vcc, s28, v44
	global_load_dwordx4 v[76:79], v[44:45], off
	s_nop 0
	v_addc_co_u32_e32 v81, vcc, 0, v45, vcc
	global_load_dwordx4 v[80:83], v[80:81], off
.LBB0_68:
	s_cmpk_eq_i32 s16, 0xf8
	s_cselect_b32 s98, 0, s14
	s_cselect_b32 s99, 0, s15
	v_lshl_add_u64 v[128:129], v[44:45], 0, s[98:99]
	v_add_co_u32_e32 v130, vcc, s28, v128
	global_load_dwordx4 v[132:135], v[128:129], off
	s_nop 0
	v_addc_co_u32_e32 v131, vcc, 0, v129, vcc
	global_load_dwordx4 v[136:139], v[130:131], off
	s_add_i32 s22, s16, 0
	v_mov_b32_e32 v4, s22
	ds_read2_b64 v[84:87], v4 offset1:32
	ds_read2_b64 v[88:91], v4 offset0:64 offset1:96
	ds_read2_b64 v[92:95], v4 offset0:128 offset1:160
	ds_read2_b64 v[96:99], v4 offset0:192 offset1:224
	s_add_i32 s16, s16, 8
	s_waitcnt lgkmcnt(3)
	v_mov_b32_e32 v100, v84
	v_mov_b32_e32 v101, v86
	s_waitcnt lgkmcnt(2)
	v_mov_b32_e32 v102, v88
	v_mov_b32_e32 v103, v90
	s_waitcnt lgkmcnt(1)
	v_mov_b32_e32 v104, v92
	v_mov_b32_e32 v105, v94
	s_waitcnt lgkmcnt(0)
	v_mov_b32_e32 v106, v96
	v_mov_b32_e32 v107, v98
	v_mov_b32_e32 v86, v85
	v_mov_b32_e32 v90, v89
	v_mov_b32_e32 v94, v93
	v_mov_b32_e32 v98, v97
	v_mov_b64_e32 v[44:45], v[128:129]
	s_waitcnt vmcnt(2)
	v_mov_b32_e32 v4, v79
	v_pk_fma_f32 v[54:55], v[100:101], v[76:77], v[54:55] op_sel_hi:[1,0,1]
	v_pk_fma_f32 v[46:47], v[100:101], v[76:77], v[46:47] op_sel:[0,1,0]
	v_pk_fma_f32 v[36:37], v[100:101], v[78:79], v[36:37] op_sel_hi:[1,0,1]
	v_pk_fma_f32 v[56:57], v[102:103], v[76:77], v[56:57] op_sel_hi:[1,0,1]
	v_pk_fma_f32 v[48:49], v[102:103], v[76:77], v[48:49] op_sel:[0,1,0]
	v_pk_fma_f32 v[38:39], v[102:103], v[78:79], v[38:39] op_sel_hi:[1,0,1]
	v_pk_fma_f32 v[60:61], v[104:105], v[76:77], v[60:61] op_sel_hi:[1,0,1]
	v_pk_fma_f32 v[52:53], v[104:105], v[76:77], v[52:53] op_sel:[0,1,0]
	v_pk_fma_f32 v[42:43], v[104:105], v[78:79], v[42:43] op_sel_hi:[1,0,1]
	v_pk_fma_f32 v[58:59], v[106:107], v[76:77], v[58:59] op_sel_hi:[1,0,1]
	v_pk_fma_f32 v[50:51], v[106:107], v[76:77], v[50:51] op_sel:[0,1,0]
	v_pk_fma_f32 v[40:41], v[106:107], v[78:79], v[40:41] op_sel_hi:[1,0,1]
	v_pk_fma_f32 v[28:29], v[100:101], v[4:5], v[28:29] op_sel_hi:[1,0,1]
	v_pk_fma_f32 v[30:31], v[102:103], v[4:5], v[30:31] op_sel_hi:[1,0,1]
	v_pk_fma_f32 v[34:35], v[104:105], v[4:5], v[34:35] op_sel_hi:[1,0,1]
	v_pk_fma_f32 v[32:33], v[106:107], v[4:5], v[32:33] op_sel_hi:[1,0,1]
	v_mov_b32_e32 v4, v83
	v_pk_fma_f32 v[54:55], v[86:87], v[80:81], v[54:55] op_sel_hi:[1,0,1]
	v_pk_fma_f32 v[46:47], v[86:87], v[80:81], v[46:47] op_sel:[0,1,0]
	v_pk_fma_f32 v[36:37], v[86:87], v[82:83], v[36:37] op_sel_hi:[1,0,1]
	v_pk_fma_f32 v[56:57], v[90:91], v[80:81], v[56:57] op_sel_hi:[1,0,1]
	v_pk_fma_f32 v[48:49], v[90:91], v[80:81], v[48:49] op_sel:[0,1,0]
	v_pk_fma_f32 v[38:39], v[90:91], v[82:83], v[38:39] op_sel_hi:[1,0,1]
	v_pk_fma_f32 v[60:61], v[94:95], v[80:81], v[60:61] op_sel_hi:[1,0,1]
	v_pk_fma_f32 v[52:53], v[94:95], v[80:81], v[52:53] op_sel:[0,1,0]
	v_pk_fma_f32 v[42:43], v[94:95], v[82:83], v[42:43] op_sel_hi:[1,0,1]
	v_pk_fma_f32 v[58:59], v[98:99], v[80:81], v[58:59] op_sel_hi:[1,0,1]
	v_pk_fma_f32 v[50:51], v[98:99], v[80:81], v[50:51] op_sel:[0,1,0]
	v_pk_fma_f32 v[40:41], v[98:99], v[82:83], v[40:41] op_sel_hi:[1,0,1]
	v_pk_fma_f32 v[28:29], v[86:87], v[4:5], v[28:29] op_sel_hi:[1,0,1]
	v_pk_fma_f32 v[30:31], v[90:91], v[4:5], v[30:31] op_sel_hi:[1,0,1]
	v_pk_fma_f32 v[34:35], v[94:95], v[4:5], v[34:35] op_sel_hi:[1,0,1]
	v_pk_fma_f32 v[32:33], v[98:99], v[4:5], v[32:33] op_sel_hi:[1,0,1]
	s_waitcnt vmcnt(0)
	v_mov_b64_e32 v[76:77], v[132:133]
	v_mov_b64_e32 v[78:79], v[134:135]
	v_mov_b64_e32 v[80:81], v[136:137]
	v_mov_b64_e32 v[82:83], v[138:139]
	s_cmpk_eq_i32 s16, 0x100
	s_cbranch_scc0 .LBB0_68
	v_cvt_f32_i32_e32 v4, s18
	s_and_b64 s[6:7], s[6:7], exec
	s_cselect_b32 s16, s29, 0x29d8000
	v_lshl_add_u64 v[44:45], v[2:3], 0, s[16:17]
	v_div_scale_f32 v27, s[6:7], v62, v62, -v4
	v_rcp_f32_e32 v63, v27
	s_lshl_b32 s16, s19, 1
	s_or_b32 s31, s16, 0x80
	s_add_i32 s19, s19, -8
	s_cmp_eq_u32 s18, s19
	v_fma_f32 v75, -v27, v63, 1.0
	s_cselect_b64 s[24:25], -1, 0
	s_ashr_i32 s19, s18, 31
	v_fmac_f32_e32 v63, v75, v63
	v_div_scale_f32 v75, vcc, -v4, v62, -v4
	s_cmp_eq_u32 s26, 0
	v_mul_f32_e32 v76, v75, v63
	s_cselect_b64 s[6:7], -1, 0
	s_sub_u32 s22, 0, s18
	v_fma_f32 v77, -v27, v76, v75
	s_subb_u32 s23, 0, s19
	v_fmac_f32_e32 v76, v77, v63
	s_or_b32 s26, s18, 1
	v_fma_f32 v27, -v27, v76, v75
	v_cvt_f32_i32_e32 v75, s26
	v_div_fmas_f32 v27, v27, v63, v76
	v_div_fixup_f32 v27, v27, v62, -v4
	v_mul_f32_e64 v76, |v67|, v27
	v_div_scale_f32 v4, s[26:27], v62, v62, -v75
	v_rcp_f32_e32 v63, v4
	v_mul_f32_e32 v76, 0x3fb8aa3b, v76
	v_exp_f32_e32 v82, v76
	s_or_b32 s26, s18, 2
	v_fma_f32 v76, -v4, v63, 1.0
	v_fmac_f32_e32 v63, v76, v63
	v_div_scale_f32 v76, vcc, -v75, v62, -v75
	v_mul_f32_e32 v77, v76, v63
	v_fma_f32 v78, -v4, v77, v76
	v_fmac_f32_e32 v77, v78, v63
	v_fma_f32 v4, -v4, v77, v76
	v_cvt_f32_i32_e32 v76, s26
	v_div_fmas_f32 v4, v4, v63, v77
	v_div_fixup_f32 v75, v4, v62, -v75
	v_mul_f32_e64 v77, |v67|, v75
	v_div_scale_f32 v4, s[26:27], v62, v62, -v76
	v_rcp_f32_e32 v63, v4
	v_mul_f32_e32 v77, 0x3fb8aa3b, v77
	v_exp_f32_e32 v83, v77
	s_or_b32 s26, s18, 3
	v_fma_f32 v77, -v4, v63, 1.0
	v_fmac_f32_e32 v63, v77, v63
	v_div_scale_f32 v77, vcc, -v76, v62, -v76
	v_mul_f32_e32 v78, v77, v63
	v_fma_f32 v79, -v4, v78, v77
	v_fmac_f32_e32 v78, v79, v63
	v_fma_f32 v4, -v4, v78, v77
	v_cvt_f32_i32_e32 v77, s26
	v_div_fmas_f32 v4, v4, v63, v78
	v_div_fixup_f32 v76, v4, v62, -v76
	v_mul_f32_e64 v78, |v67|, v76
	v_div_scale_f32 v4, s[26:27], v62, v62, -v77
	v_rcp_f32_e32 v63, v4
	v_mul_f32_e32 v78, 0x3fb8aa3b, v78
	v_exp_f32_e32 v84, v78
	s_or_b32 s26, s18, 4
	v_fma_f32 v78, -v4, v63, 1.0
	v_fmac_f32_e32 v63, v78, v63
	v_div_scale_f32 v78, vcc, -v77, v62, -v77
	v_mul_f32_e32 v79, v78, v63
	v_fma_f32 v80, -v4, v79, v78
	v_fmac_f32_e32 v79, v80, v63
	v_fma_f32 v4, -v4, v79, v78
	v_cvt_f32_i32_e32 v78, s26
	v_div_fmas_f32 v4, v4, v63, v79
	v_div_fixup_f32 v77, v4, v62, -v77
	v_mul_f32_e64 v79, |v67|, v77
	v_div_scale_f32 v4, s[26:27], v62, v62, -v78
	v_rcp_f32_e32 v63, v4
	v_mul_f32_e32 v79, 0x3fb8aa3b, v79
	v_exp_f32_e32 v85, v79
	s_or_b32 s26, s18, 5
	v_fma_f32 v79, -v4, v63, 1.0
	v_fmac_f32_e32 v63, v79, v63
	v_div_scale_f32 v79, vcc, -v78, v62, -v78
	v_mul_f32_e32 v80, v79, v63
	v_fma_f32 v81, -v4, v80, v79
	v_fmac_f32_e32 v80, v81, v63
	v_fma_f32 v4, -v4, v80, v79
	v_cvt_f32_i32_e32 v79, s26
	v_div_fmas_f32 v4, v4, v63, v80
	v_div_fixup_f32 v78, v4, v62, -v78
	v_mul_f32_e64 v80, |v67|, v78
	v_div_scale_f32 v4, s[26:27], v62, v62, -v79
	v_rcp_f32_e32 v63, v4
	v_mul_f32_e32 v80, 0x3fb8aa3b, v80
	v_exp_f32_e32 v86, v80
	s_or_b32 s26, s18, 6
	v_fma_f32 v80, -v4, v63, 1.0
	v_fmac_f32_e32 v63, v80, v63
	v_div_scale_f32 v80, vcc, -v79, v62, -v79
	v_mul_f32_e32 v81, v80, v63
	v_fma_f32 v87, -v4, v81, v80
	v_fmac_f32_e32 v81, v87, v63
	v_fma_f32 v4, -v4, v81, v80
	v_cvt_f32_i32_e32 v80, s26
	v_div_fmas_f32 v4, v4, v63, v81
	v_div_fixup_f32 v79, v4, v62, -v79
	v_mul_f32_e64 v81, |v67|, v79
	v_div_scale_f32 v4, s[26:27], v62, v62, -v80
	v_rcp_f32_e32 v63, v4
	v_mul_f32_e32 v81, 0x3fb8aa3b, v81
	v_exp_f32_e32 v87, v81
	s_or_b32 s26, s18, 7
	v_fma_f32 v81, -v4, v63, 1.0
	v_fmac_f32_e32 v63, v81, v63
	v_div_scale_f32 v81, vcc, -v80, v62, -v80
	v_mul_f32_e32 v88, v81, v63
	v_fma_f32 v89, -v4, v88, v81
	v_fmac_f32_e32 v88, v89, v63
	v_fma_f32 v4, -v4, v88, v81
	v_cvt_f32_i32_e32 v81, s26
	v_div_fmas_f32 v4, v4, v63, v88
	v_div_fixup_f32 v80, v4, v62, -v80
	v_mul_f32_e64 v88, |v67|, v80
	v_div_scale_f32 v4, s[26:27], v62, v62, -v81
	v_rcp_f32_e32 v63, v4
	v_mul_f32_e32 v88, 0x3fb8aa3b, v88
	v_exp_f32_e32 v88, v88
	v_pk_mul_f32 v[56:57], v[84:85], v[56:57]
	v_fma_f32 v89, -v4, v63, 1.0
	v_fmac_f32_e32 v63, v89, v63
	v_div_scale_f32 v89, vcc, -v81, v62, -v81
	v_mul_f32_e32 v90, v89, v63
	v_fma_f32 v91, -v4, v90, v89
	v_fmac_f32_e32 v90, v91, v63
	v_fma_f32 v4, -v4, v90, v89
	v_div_fmas_f32 v4, v4, v63, v90
	v_div_fixup_f32 v81, v4, v62, -v81
	v_mul_f32_e64 v4, |v67|, v81
	v_mul_f32_e32 v4, 0x3fb8aa3b, v4
	v_exp_f32_e32 v89, v4
	v_mul_u32_u24_e32 v4, s31, v68
	v_lshlrev_b32_e32 v4, 1, v4
	v_pk_mul_f32 v[62:63], v[82:83], v[54:55]
	v_lshl_add_u64 v[54:55], v[44:45], 0, v[4:5]
	v_cndmask_b32_e64 v4, 0, 1, s[6:7]
	v_pk_mul_f32 v[60:61], v[86:87], v[60:61]
	v_pk_mul_f32 v[58:59], v[88:89], v[58:59]
	v_cmp_ne_u32_e64 s[6:7], 1, v4
	s_and_saveexec_b64 s[26:27], s[4:5]
	s_xor_b64 s[26:27], exec, s[26:27]
	s_cbranch_execz .LBB0_71
	v_cvt_pk_bf16_f32 v82, v62, v63
	v_cvt_pk_bf16_f32 v83, v56, v57
	v_lshl_add_u64 v[56:57], v[54:55], 0, s[16:17]
	v_lshl_add_u64 v[56:57], s[18:19], 1, v[56:57]
	s_and_b64 vcc, exec, s[6:7]
	v_cndmask_b32_e64 v4, v59, 0, s[24:25]
	v_cvt_pk_bf16_f32 v84, v60, v61
	v_cvt_pk_bf16_f32 v85, v58, v4
	global_store_dwordx4 v[56:57], v[82:85], off offset:144
	s_cbranch_vccz .LBB0_74

.LBB0_505:
	s_ashr_i32 s9, s7, 31
	s_xor_b32 s8, s8, s9
	s_sub_i32 s8, s8, s9
	s_mul_i32 s9, s8, s19
	s_sub_i32 s9, s6, s9
	s_lshl_b32 s9, s9, 3
	s_and_b32 s6, s59, 48
	s_max_i32 s10, s9, 4
	v_sub_u32_e64 v64, s6, 8 clamp
	s_add_i32 s10, s10, -4
	s_and_b32 s60, s7, 7
	s_lshl_b32 s11, s8, s52
	v_min_u32_e32 v168, 32, v64
	s_min_i32 s10, s10, s53
	s_add_i32 s7, s9, s21
	s_lshl_b32 s9, s7, 6
	s_add_i32 s9, s9, s11
	s_or_b32 s9, s9, s6
	v_or_b32_e32 v142, s9, v139
	v_ashrrev_i32_e32 v143, 31, v142
	v_readlane_b32 s28, v250, 8
	v_lshlrev_b64 v[64:65], 11, v[142:143]
	v_readlane_b32 s29, v250, 9
	s_lshl_b32 s36, s60, 7
	s_max_i32 s8, s7, 4
	v_lshl_add_u64 v[64:65], s[28:29], 0, v[64:65]
	v_lshl_add_u64 v[64:65], v[64:65], 0, s[36:37]
	v_lshl_add_u64 v[68:69], v[64:65], 0, v[144:145]
	global_load_dwordx4 v[64:67], v[68:69], off
	global_load_dwordx4 v[128:131], v[68:69], off offset:64
	s_add_i32 s8, s8, -4
	s_min_i32 s8, s8, s54
	s_sub_i32 s36, s8, s10
	v_lshl_add_u32 v72, s36, 12, v160
	v_add_u32_e32 v169, v72, v161
	s_waitcnt lgkmcnt(0)
	s_barrier
	v_add_u32_e32 v170, v72, v162
	ds_read_b128 v[196:199], v169
	ds_read_b128 v[200:203], v170
	ds_read_b128 v[204:207], v169 offset:2048
	ds_read_b128 v[208:211], v170 offset:2048
	ds_read_b128 v[212:215], v169 offset:4096
	ds_read_b128 v[216:219], v170 offset:4096
	s_mul_i32 s9, s60, 0x780
	s_sub_i32 s7, s8, s7
	s_add_i32 s9, s9, 0
	s_mulk_i32 s7, 0x7c
	s_add_i32 s61, s9, s7
	s_add_i32 s61, s61, 0x1f400
	v_or_b32_e32 v189, s6, v139
	s_waitcnt vmcnt(1) lgkmcnt(4)
	v_mfma_f32_16x16x32_bf16 v[124:127], v[196:199], v[64:67], 0
	s_waitcnt vmcnt(0)
	v_mfma_f32_16x16x32_bf16 v[124:127], v[200:203], v[128:131], v[124:127]
	ds_read_b128 v[196:199], v169 offset:6144
	ds_read_b128 v[200:203], v170 offset:6144
	s_waitcnt lgkmcnt(4)
	v_mfma_f32_16x16x32_bf16 v[120:123], v[204:207], v[64:67], 0
	v_mfma_f32_16x16x32_bf16 v[120:123], v[208:211], v[128:131], v[120:123]
	ds_read_b128 v[204:207], v169 offset:8192
	ds_read_b128 v[208:211], v170 offset:8192
	s_waitcnt lgkmcnt(4)
	v_mfma_f32_16x16x32_bf16 v[116:119], v[212:215], v[64:67], 0
	v_mfma_f32_16x16x32_bf16 v[116:119], v[216:219], v[128:131], v[116:119]
	ds_read_b128 v[212:215], v169 offset:10240
	ds_read_b128 v[216:219], v170 offset:10240
	s_waitcnt lgkmcnt(4)
	v_mfma_f32_16x16x32_bf16 v[112:115], v[196:199], v[64:67], 0
	v_mfma_f32_16x16x32_bf16 v[112:115], v[200:203], v[128:131], v[112:115]
	ds_read_b128 v[196:199], v169 offset:12288
	ds_read_b128 v[200:203], v170 offset:12288
	s_waitcnt lgkmcnt(4)
	v_mfma_f32_16x16x32_bf16 v[108:111], v[204:207], v[64:67], 0
	v_mfma_f32_16x16x32_bf16 v[108:111], v[208:211], v[128:131], v[108:111]
	ds_read_b128 v[204:207], v169 offset:14336
	ds_read_b128 v[208:211], v170 offset:14336
	s_waitcnt lgkmcnt(4)
	v_mfma_f32_16x16x32_bf16 v[104:107], v[212:215], v[64:67], 0
	v_mfma_f32_16x16x32_bf16 v[104:107], v[216:219], v[128:131], v[104:107]
	ds_read_b128 v[212:215], v169 offset:16384
	ds_read_b128 v[216:219], v170 offset:16384
	s_waitcnt lgkmcnt(4)
	v_mfma_f32_16x16x32_bf16 v[100:103], v[196:199], v[64:67], 0
	v_mfma_f32_16x16x32_bf16 v[100:103], v[200:203], v[128:131], v[100:103]
	ds_read_b128 v[196:199], v169 offset:18432
	ds_read_b128 v[200:203], v170 offset:18432
	s_waitcnt lgkmcnt(4)
	v_mfma_f32_16x16x32_bf16 v[96:99], v[204:207], v[64:67], 0
	v_mfma_f32_16x16x32_bf16 v[96:99], v[208:211], v[128:131], v[96:99]
	ds_read_b128 v[204:207], v169 offset:20480
	ds_read_b128 v[208:211], v170 offset:20480
	s_waitcnt lgkmcnt(4)
	v_mfma_f32_16x16x32_bf16 v[92:95], v[212:215], v[64:67], 0
	v_mfma_f32_16x16x32_bf16 v[92:95], v[216:219], v[128:131], v[92:95]
	ds_read_b128 v[212:215], v169 offset:22528
	ds_read_b128 v[216:219], v170 offset:22528
	s_waitcnt lgkmcnt(4)
	v_mfma_f32_16x16x32_bf16 v[88:91], v[196:199], v[64:67], 0
	v_mfma_f32_16x16x32_bf16 v[88:91], v[200:203], v[128:131], v[88:91]
	ds_read_b128 v[196:199], v169 offset:24576
	ds_read_b128 v[200:203], v170 offset:24576
	s_waitcnt lgkmcnt(4)
	v_mfma_f32_16x16x32_bf16 v[84:87], v[204:207], v[64:67], 0
	v_mfma_f32_16x16x32_bf16 v[84:87], v[208:211], v[128:131], v[84:87]
	ds_read_b128 v[204:207], v169 offset:26624
	ds_read_b128 v[208:211], v170 offset:26624
	s_waitcnt lgkmcnt(4)
	v_mfma_f32_16x16x32_bf16 v[76:79], v[212:215], v[64:67], 0
	v_mfma_f32_16x16x32_bf16 v[76:79], v[216:219], v[128:131], v[76:79]
	ds_read_b128 v[212:215], v169 offset:28672
	ds_read_b128 v[216:219], v170 offset:28672
	s_waitcnt lgkmcnt(4)
	v_mfma_f32_16x16x32_bf16 v[80:83], v[196:199], v[64:67], 0
	v_mfma_f32_16x16x32_bf16 v[80:83], v[200:203], v[128:131], v[80:83]
	ds_read_b128 v[196:199], v169 offset:30720
	ds_read_b128 v[200:203], v170 offset:30720
	s_waitcnt lgkmcnt(4)
	v_mfma_f32_16x16x32_bf16 v[72:75], v[204:207], v[64:67], 0
	v_mfma_f32_16x16x32_bf16 v[72:75], v[208:211], v[128:131], v[72:75]
	s_waitcnt lgkmcnt(2)
	v_mfma_f32_16x16x32_bf16 v[68:71], v[212:215], v[64:67], 0
	v_mfma_f32_16x16x32_bf16 v[68:71], v[216:219], v[128:131], v[68:71]
	s_waitcnt lgkmcnt(0)
	v_mfma_f32_16x16x32_bf16 v[64:67], v[196:199], v[64:67], 0
	v_mfma_f32_16x16x32_bf16 v[64:67], v[200:203], v[128:131], v[64:67]
	v_max_i32_e32 v128, 8, v189
	v_add_u32_e32 v128, -8, v128
	v_min_u32_e32 v190, 48, v128
	v_add_u32_e32 v192, v168, v138
	v_add_u32_e32 v191, 16, v190
	v_mov_b32_e32 v188, 0xf149f2ca
	v_cmp_ge_u32_e32 vcc, v192, v190
	v_cmp_lt_u32_e64 s[6:7], v192, v191
	v_sub_u32_e32 v194, v192, v189
	v_max_i32_e32 v194, -15, v194
	v_add_u32_e32 v194, 15, v194
	s_and_b64 s[8:9], vcc, s[6:7]
	v_min_u32_e32 v194, 30, v194
	v_lshl_add_u32 v196, v194, 2, s61
	v_add_u32_e32 v193, 1, v192
	v_cmp_ge_u32_e32 vcc, v193, v190
	v_cmp_lt_u32_e64 s[6:7], v193, v191
	v_sub_u32_e32 v194, v193, v189
	v_max_i32_e32 v194, -15, v194
	v_add_u32_e32 v194, 15, v194
	s_and_b64 s[10:11], vcc, s[6:7]
	v_min_u32_e32 v194, 30, v194
	v_lshl_add_u32 v197, v194, 2, s61
	v_add_u32_e32 v193, 2, v192
	v_cmp_ge_u32_e32 vcc, v193, v190
	v_cmp_lt_u32_e64 s[6:7], v193, v191
	v_sub_u32_e32 v194, v193, v189
	v_max_i32_e32 v194, -15, v194
	v_add_u32_e32 v194, 15, v194
	s_and_b64 s[22:23], vcc, s[6:7]
	v_min_u32_e32 v194, 30, v194
	v_lshl_add_u32 v198, v194, 2, s61
	v_add_u32_e32 v193, 3, v192
	v_cmp_ge_u32_e32 vcc, v193, v190
	v_cmp_lt_u32_e64 s[6:7], v193, v191
	v_sub_u32_e32 v194, v193, v189
	v_max_i32_e32 v194, -15, v194
	v_add_u32_e32 v194, 15, v194
	s_and_b64 s[28:29], vcc, s[6:7]
	v_min_u32_e32 v194, 30, v194
	v_lshl_add_u32 v199, v194, 2, s61
	v_add_u32_e32 v193, 16, v192
	v_cmp_ge_u32_e32 vcc, v193, v190
	v_cmp_lt_u32_e64 s[6:7], v193, v191
	v_sub_u32_e32 v194, v193, v189
	v_max_i32_e32 v194, -15, v194
	v_add_u32_e32 v194, 15, v194
	s_and_b64 s[44:45], vcc, s[6:7]
	v_min_u32_e32 v194, 30, v194
	v_lshl_add_u32 v200, v194, 2, s61
	v_add_u32_e32 v193, 17, v192
	v_cmp_ge_u32_e32 vcc, v193, v190
	v_cmp_lt_u32_e64 s[6:7], v193, v191
	v_sub_u32_e32 v194, v193, v189
	v_max_i32_e32 v194, -15, v194
	v_add_u32_e32 v194, 15, v194
	s_and_b64 s[48:49], vcc, s[6:7]
	v_min_u32_e32 v194, 30, v194
	v_lshl_add_u32 v201, v194, 2, s61
	v_add_u32_e32 v193, 18, v192
	v_cmp_ge_u32_e32 vcc, v193, v190
	v_cmp_lt_u32_e64 s[6:7], v193, v191
	v_sub_u32_e32 v194, v193, v189
	v_max_i32_e32 v194, -15, v194
	v_add_u32_e32 v194, 15, v194
	s_and_b64 s[50:51], vcc, s[6:7]
	v_min_u32_e32 v194, 30, v194
	v_lshl_add_u32 v202, v194, 2, s61
	v_add_u32_e32 v193, 19, v192
	v_cmp_ge_u32_e32 vcc, v193, v190
	v_cmp_lt_u32_e64 s[6:7], v193, v191
	v_sub_u32_e32 v194, v193, v189
	v_max_i32_e32 v194, -15, v194
	v_add_u32_e32 v194, 15, v194
	s_and_b64 s[98:99], vcc, s[6:7]
	v_min_u32_e32 v194, 30, v194
	v_lshl_add_u32 v203, v194, 2, s61
	ds_read_b32 v204, v196 offset:868
	ds_read_b32 v205, v197 offset:868
	ds_read_b32 v206, v198 offset:868
	ds_read_b32 v207, v199 offset:868
	ds_read_b32 v208, v200 offset:868
	ds_read_b32 v209, v201 offset:868
	ds_read_b32 v210, v202 offset:868
	ds_read_b32 v211, v203 offset:868
	ds_read_b32 v212, v196 offset:992
	ds_read_b32 v213, v197 offset:992
	ds_read_b32 v214, v198 offset:992
	ds_read_b32 v215, v199 offset:992
	ds_read_b32 v216, v200 offset:992
	ds_read_b32 v217, v201 offset:992
	ds_read_b32 v218, v202 offset:992
	ds_read_b32 v219, v203 offset:992
	s_waitcnt lgkmcnt(8)
	v_fmac_f32_e32 v204, 0x3e000000, v124
	v_cndmask_b32_e64 v129, v188, v204, s[8:9]
	v_fmac_f32_e32 v205, 0x3e000000, v125
	v_cndmask_b32_e64 v128, v188, v205, s[10:11]
	v_fmac_f32_e32 v206, 0x3e000000, v126
	v_cndmask_b32_e64 v125, v188, v206, s[22:23]
	v_fmac_f32_e32 v207, 0x3e000000, v127
	v_cndmask_b32_e64 v124, v188, v207, s[28:29]
	v_fmac_f32_e32 v208, 0x3e000000, v120
	v_cndmask_b32_e64 v127, v188, v208, s[44:45]
	v_fmac_f32_e32 v209, 0x3e000000, v121
	v_cndmask_b32_e64 v126, v188, v209, s[48:49]
	v_fmac_f32_e32 v210, 0x3e000000, v122
	v_cndmask_b32_e64 v121, v188, v210, s[50:51]
	v_fmac_f32_e32 v211, 0x3e000000, v123
	v_cndmask_b32_e64 v120, v188, v211, s[98:99]
	ds_read_b32 v204, v196 offset:1116
	ds_read_b32 v205, v197 offset:1116
	ds_read_b32 v206, v198 offset:1116
	ds_read_b32 v207, v199 offset:1116
	ds_read_b32 v208, v200 offset:1116
	ds_read_b32 v209, v201 offset:1116
	ds_read_b32 v210, v202 offset:1116
	ds_read_b32 v211, v203 offset:1116
	s_waitcnt lgkmcnt(8)
	v_fmac_f32_e32 v212, 0x3e000000, v116
	v_cndmask_b32_e64 v123, v188, v212, s[8:9]
	v_fmac_f32_e32 v213, 0x3e000000, v117
	v_cndmask_b32_e64 v122, v188, v213, s[10:11]
	v_fmac_f32_e32 v214, 0x3e000000, v118
	v_cndmask_b32_e64 v117, v188, v214, s[22:23]
	v_fmac_f32_e32 v215, 0x3e000000, v119
	v_cndmask_b32_e64 v116, v188, v215, s[28:29]
	v_fmac_f32_e32 v216, 0x3e000000, v112
	v_cndmask_b32_e64 v119, v188, v216, s[44:45]
	v_fmac_f32_e32 v217, 0x3e000000, v113
	v_cndmask_b32_e64 v118, v188, v217, s[48:49]
	v_fmac_f32_e32 v218, 0x3e000000, v114
	v_cndmask_b32_e64 v113, v188, v218, s[50:51]
	v_fmac_f32_e32 v219, 0x3e000000, v115
	v_cndmask_b32_e64 v112, v188, v219, s[98:99]
	ds_read_b32 v212, v196 offset:1240
	ds_read_b32 v213, v197 offset:1240
	ds_read_b32 v214, v198 offset:1240
	ds_read_b32 v215, v199 offset:1240
	ds_read_b32 v216, v200 offset:1240
	ds_read_b32 v217, v201 offset:1240
	ds_read_b32 v218, v202 offset:1240
	ds_read_b32 v219, v203 offset:1240
	s_waitcnt lgkmcnt(8)
	v_fmac_f32_e32 v204, 0x3e000000, v108
	v_cndmask_b32_e64 v115, v188, v204, s[8:9]
	v_fmac_f32_e32 v205, 0x3e000000, v109
	v_cndmask_b32_e64 v114, v188, v205, s[10:11]
	v_fmac_f32_e32 v206, 0x3e000000, v110
	v_cndmask_b32_e64 v109, v188, v206, s[22:23]
	v_fmac_f32_e32 v207, 0x3e000000, v111
	v_cndmask_b32_e64 v108, v188, v207, s[28:29]
	v_fmac_f32_e32 v208, 0x3e000000, v104
	v_cndmask_b32_e64 v111, v188, v208, s[44:45]
	v_fmac_f32_e32 v209, 0x3e000000, v105
	v_cndmask_b32_e64 v110, v188, v209, s[48:49]
	v_fmac_f32_e32 v210, 0x3e000000, v106
	v_cndmask_b32_e64 v105, v188, v210, s[50:51]
	v_fmac_f32_e32 v211, 0x3e000000, v107
	v_cndmask_b32_e64 v104, v188, v211, s[98:99]
	ds_read_b32 v204, v196 offset:1364
	ds_read_b32 v205, v197 offset:1364
	ds_read_b32 v206, v198 offset:1364
	ds_read_b32 v207, v199 offset:1364
	ds_read_b32 v208, v200 offset:1364
	ds_read_b32 v209, v201 offset:1364
	ds_read_b32 v210, v202 offset:1364
	ds_read_b32 v211, v203 offset:1364
	s_waitcnt lgkmcnt(8)
	v_fmac_f32_e32 v212, 0x3e000000, v100
	v_cndmask_b32_e64 v107, v188, v212, s[8:9]
	v_fmac_f32_e32 v213, 0x3e000000, v101
	v_cndmask_b32_e64 v106, v188, v213, s[10:11]
	v_fmac_f32_e32 v214, 0x3e000000, v102
	v_cndmask_b32_e64 v101, v188, v214, s[22:23]
	v_fmac_f32_e32 v215, 0x3e000000, v103
	v_cndmask_b32_e64 v100, v188, v215, s[28:29]
	v_fmac_f32_e32 v216, 0x3e000000, v96
	v_cndmask_b32_e64 v103, v188, v216, s[44:45]
	v_fmac_f32_e32 v217, 0x3e000000, v97
	v_cndmask_b32_e64 v102, v188, v217, s[48:49]
	v_fmac_f32_e32 v218, 0x3e000000, v98
	v_cndmask_b32_e64 v97, v188, v218, s[50:51]
	v_fmac_f32_e32 v219, 0x3e000000, v99
	v_cndmask_b32_e64 v96, v188, v219, s[98:99]
	ds_read_b32 v212, v196 offset:1488
	ds_read_b32 v213, v197 offset:1488
	ds_read_b32 v214, v198 offset:1488
	ds_read_b32 v215, v199 offset:1488
	ds_read_b32 v216, v200 offset:1488
	ds_read_b32 v217, v201 offset:1488
	ds_read_b32 v218, v202 offset:1488
	ds_read_b32 v219, v203 offset:1488
	s_waitcnt lgkmcnt(8)
	v_fmac_f32_e32 v204, 0x3e000000, v92
	v_cndmask_b32_e64 v99, v188, v204, s[8:9]
	v_fmac_f32_e32 v205, 0x3e000000, v93
	v_cndmask_b32_e64 v98, v188, v205, s[10:11]
	v_fmac_f32_e32 v206, 0x3e000000, v94
	v_cndmask_b32_e64 v93, v188, v206, s[22:23]
	v_fmac_f32_e32 v207, 0x3e000000, v95
	v_cndmask_b32_e64 v92, v188, v207, s[28:29]
	v_fmac_f32_e32 v208, 0x3e000000, v88
	v_cndmask_b32_e64 v95, v188, v208, s[44:45]
	v_fmac_f32_e32 v209, 0x3e000000, v89
	v_cndmask_b32_e64 v94, v188, v209, s[48:49]
	v_fmac_f32_e32 v210, 0x3e000000, v90
	v_cndmask_b32_e64 v89, v188, v210, s[50:51]
	v_fmac_f32_e32 v211, 0x3e000000, v91
	v_cndmask_b32_e64 v88, v188, v211, s[98:99]
	ds_read_b32 v204, v196 offset:1612
	ds_read_b32 v205, v197 offset:1612
	ds_read_b32 v206, v198 offset:1612
	ds_read_b32 v207, v199 offset:1612
	ds_read_b32 v208, v200 offset:1612
	ds_read_b32 v209, v201 offset:1612
	ds_read_b32 v210, v202 offset:1612
	ds_read_b32 v211, v203 offset:1612
	s_waitcnt lgkmcnt(8)
	v_fmac_f32_e32 v212, 0x3e000000, v84
	v_cndmask_b32_e64 v91, v188, v212, s[8:9]
	v_fmac_f32_e32 v213, 0x3e000000, v85
	v_cndmask_b32_e64 v90, v188, v213, s[10:11]
	v_fmac_f32_e32 v214, 0x3e000000, v86
	v_cndmask_b32_e64 v85, v188, v214, s[22:23]
	v_fmac_f32_e32 v215, 0x3e000000, v87
	v_cndmask_b32_e64 v84, v188, v215, s[28:29]
	v_fmac_f32_e32 v216, 0x3e000000, v76
	v_cndmask_b32_e64 v87, v188, v216, s[44:45]
	v_fmac_f32_e32 v217, 0x3e000000, v77
	v_cndmask_b32_e64 v86, v188, v217, s[48:49]
	v_fmac_f32_e32 v218, 0x3e000000, v78
	v_cndmask_b32_e64 v77, v188, v218, s[50:51]
	v_fmac_f32_e32 v219, 0x3e000000, v79
	v_cndmask_b32_e64 v76, v188, v219, s[98:99]
	ds_read_b32 v212, v196 offset:1736
	ds_read_b32 v213, v197 offset:1736
	ds_read_b32 v214, v198 offset:1736
	ds_read_b32 v215, v199 offset:1736
	ds_read_b32 v216, v200 offset:1736
	ds_read_b32 v217, v201 offset:1736
	ds_read_b32 v218, v202 offset:1736
	ds_read_b32 v219, v203 offset:1736
	s_waitcnt lgkmcnt(8)
	v_fmac_f32_e32 v204, 0x3e000000, v80
	v_cndmask_b32_e64 v79, v188, v204, s[8:9]
	v_fmac_f32_e32 v205, 0x3e000000, v81
	v_cndmask_b32_e64 v78, v188, v205, s[10:11]
	v_fmac_f32_e32 v206, 0x3e000000, v82
	v_cndmask_b32_e64 v81, v188, v206, s[22:23]
	v_fmac_f32_e32 v207, 0x3e000000, v83
	v_cndmask_b32_e64 v80, v188, v207, s[28:29]
	v_fmac_f32_e32 v208, 0x3e000000, v72
	v_cndmask_b32_e64 v83, v188, v208, s[44:45]
	v_fmac_f32_e32 v209, 0x3e000000, v73
	v_cndmask_b32_e64 v82, v188, v209, s[48:49]
	v_fmac_f32_e32 v210, 0x3e000000, v74
	v_cndmask_b32_e64 v73, v188, v210, s[50:51]
	v_fmac_f32_e32 v211, 0x3e000000, v75
	v_cndmask_b32_e64 v72, v188, v211, s[98:99]
	s_waitcnt lgkmcnt(0)
	v_fmac_f32_e32 v212, 0x3e000000, v68
	v_cndmask_b32_e64 v75, v188, v212, s[8:9]
	v_fmac_f32_e32 v213, 0x3e000000, v69
	v_cndmask_b32_e64 v74, v188, v213, s[10:11]
	v_fmac_f32_e32 v214, 0x3e000000, v70
	v_cndmask_b32_e64 v69, v188, v214, s[22:23]
	v_fmac_f32_e32 v215, 0x3e000000, v71
	v_cndmask_b32_e64 v68, v188, v215, s[28:29]
	v_fmac_f32_e32 v216, 0x3e000000, v64
	v_cndmask_b32_e64 v71, v188, v216, s[44:45]
	v_fmac_f32_e32 v217, 0x3e000000, v65
	v_cndmask_b32_e64 v70, v188, v217, s[48:49]
	v_fmac_f32_e32 v218, 0x3e000000, v66
	v_cndmask_b32_e64 v65, v188, v218, s[50:51]
	v_fmac_f32_e32 v219, 0x3e000000, v67
	v_cndmask_b32_e64 v64, v188, v219, s[98:99]
	s_mov_b32 s6, 0xff61b1e6
	v_max3_f32 v66, v129, s6, v128
	v_max3_f32 v66, v66, v125, v124
	v_max3_f32 v66, v66, v127, v126
	v_max3_f32 v66, v66, v121, v120
	v_max3_f32 v66, v66, v123, v122
	v_max3_f32 v66, v66, v117, v116
	v_max3_f32 v66, v66, v119, v118
	v_max3_f32 v66, v66, v113, v112
	v_max3_f32 v66, v66, v115, v114
	v_max3_f32 v66, v66, v109, v108
	v_max3_f32 v66, v66, v111, v110
	v_max3_f32 v66, v66, v105, v104
	v_max3_f32 v66, v66, v107, v106
	v_max3_f32 v66, v66, v101, v100
	v_max3_f32 v66, v66, v103, v102
	v_max3_f32 v66, v66, v97, v96
	v_max3_f32 v66, v66, v99, v98
	v_max3_f32 v66, v66, v93, v92
	v_max3_f32 v66, v66, v95, v94
	v_max3_f32 v66, v66, v89, v88
	v_max3_f32 v66, v66, v91, v90
	v_max3_f32 v66, v66, v85, v84
	v_max3_f32 v66, v66, v87, v86
	v_max3_f32 v66, v66, v77, v76
	v_max3_f32 v66, v66, v79, v78
	v_max3_f32 v66, v66, v81, v80
	v_max3_f32 v66, v66, v83, v82
	v_max3_f32 v66, v66, v73, v72
	v_max3_f32 v66, v66, v75, v74
	v_max3_f32 v66, v66, v69, v68
	v_max3_f32 v66, v66, v71, v70
	v_max3_f32 v66, v66, v65, v64
	ds_bpermute_b32 v67, v163, v66
	s_waitcnt lgkmcnt(0)
	v_max_f32_e32 v67, v67, v67
	v_max_f32_e32 v66, v66, v67
	ds_bpermute_b32 v67, v164, v66
	s_waitcnt lgkmcnt(0)
	v_max_f32_e32 v67, v67, v67
	v_max_f32_e32 v66, v66, v67
	v_sub_f32_e32 v67, v129, v66
	v_sub_f32_e32 v128, v128, v66
	v_mul_f32_e32 v67, 0x3fb8aa3b, v67
	v_sub_f32_e32 v125, v125, v66
	v_mul_f32_e32 v128, 0x3fb8aa3b, v128
	v_exp_f32_e32 v67, v67
	v_sub_f32_e32 v124, v124, v66
	v_mul_f32_e32 v125, 0x3fb8aa3b, v125
	v_exp_f32_e32 v128, v128
	v_sub_f32_e32 v127, v127, v66
	v_mul_f32_e32 v124, 0x3fb8aa3b, v124
	v_exp_f32_e32 v125, v125
	v_mul_f32_e32 v127, 0x3fb8aa3b, v127
	v_exp_f32_e32 v124, v124
	v_sub_f32_e32 v126, v126, v66
	v_add_f32_e32 v129, 0, v67
	v_exp_f32_e32 v127, v127
	v_mul_f32_e32 v126, 0x3fb8aa3b, v126
	v_sub_f32_e32 v121, v121, v66
	v_add_f32_e32 v129, v128, v129
	v_exp_f32_e32 v126, v126
	v_mul_f32_e32 v121, 0x3fb8aa3b, v121
	v_sub_f32_e32 v120, v120, v66
	v_add_f32_e32 v129, v125, v129
	v_exp_f32_e32 v121, v121
	v_mul_f32_e32 v120, 0x3fb8aa3b, v120
	v_sub_f32_e32 v123, v123, v66
	v_add_f32_e32 v129, v124, v129
	v_exp_f32_e32 v120, v120
	v_mul_f32_e32 v123, 0x3fb8aa3b, v123
	v_sub_f32_e32 v122, v122, v66
	v_add_f32_e32 v129, v127, v129
	v_exp_f32_e32 v123, v123
	v_mul_f32_e32 v122, 0x3fb8aa3b, v122
	v_sub_f32_e32 v117, v117, v66
	v_add_f32_e32 v129, v126, v129
	v_exp_f32_e32 v122, v122
	v_mul_f32_e32 v117, 0x3fb8aa3b, v117
	v_sub_f32_e32 v116, v116, v66
	v_add_f32_e32 v129, v121, v129
	v_exp_f32_e32 v117, v117
	v_mul_f32_e32 v116, 0x3fb8aa3b, v116
	v_sub_f32_e32 v119, v119, v66
	v_add_f32_e32 v129, v120, v129
	v_exp_f32_e32 v116, v116
	v_mul_f32_e32 v119, 0x3fb8aa3b, v119
	v_sub_f32_e32 v118, v118, v66
	v_add_f32_e32 v129, v123, v129
	v_exp_f32_e32 v119, v119
	v_mul_f32_e32 v118, 0x3fb8aa3b, v118
	v_sub_f32_e32 v113, v113, v66
	v_add_f32_e32 v129, v122, v129
	v_exp_f32_e32 v118, v118
	v_mul_f32_e32 v113, 0x3fb8aa3b, v113
	v_sub_f32_e32 v112, v112, v66
	v_add_f32_e32 v129, v117, v129
	v_exp_f32_e32 v113, v113
	v_mul_f32_e32 v112, 0x3fb8aa3b, v112
	v_sub_f32_e32 v115, v115, v66
	v_add_f32_e32 v129, v116, v129
	v_exp_f32_e32 v112, v112
	v_mul_f32_e32 v115, 0x3fb8aa3b, v115
	v_sub_f32_e32 v114, v114, v66
	v_add_f32_e32 v129, v119, v129
	v_exp_f32_e32 v115, v115
	v_mul_f32_e32 v114, 0x3fb8aa3b, v114
	v_sub_f32_e32 v109, v109, v66
	v_add_f32_e32 v129, v118, v129
	v_exp_f32_e32 v114, v114
	v_mul_f32_e32 v109, 0x3fb8aa3b, v109
	v_sub_f32_e32 v108, v108, v66
	v_add_f32_e32 v129, v113, v129
	v_exp_f32_e32 v109, v109
	v_mul_f32_e32 v108, 0x3fb8aa3b, v108
	v_sub_f32_e32 v111, v111, v66
	v_add_f32_e32 v129, v112, v129
	v_exp_f32_e32 v108, v108
	v_mul_f32_e32 v111, 0x3fb8aa3b, v111
	v_sub_f32_e32 v110, v110, v66
	v_add_f32_e32 v129, v115, v129
	v_exp_f32_e32 v111, v111
	v_mul_f32_e32 v110, 0x3fb8aa3b, v110
	v_sub_f32_e32 v105, v105, v66
	v_add_f32_e32 v129, v114, v129
	v_exp_f32_e32 v110, v110
	v_mul_f32_e32 v105, 0x3fb8aa3b, v105
	v_sub_f32_e32 v104, v104, v66
	v_add_f32_e32 v129, v109, v129
	v_exp_f32_e32 v105, v105
	v_mul_f32_e32 v104, 0x3fb8aa3b, v104
	v_sub_f32_e32 v107, v107, v66
	v_add_f32_e32 v129, v108, v129
	v_exp_f32_e32 v104, v104
	v_mul_f32_e32 v107, 0x3fb8aa3b, v107
	v_sub_f32_e32 v106, v106, v66
	v_add_f32_e32 v129, v111, v129
	v_exp_f32_e32 v107, v107
	v_mul_f32_e32 v106, 0x3fb8aa3b, v106
	v_sub_f32_e32 v101, v101, v66
	v_add_f32_e32 v129, v110, v129
	v_exp_f32_e32 v106, v106
	v_mul_f32_e32 v101, 0x3fb8aa3b, v101
	v_sub_f32_e32 v100, v100, v66
	v_add_f32_e32 v129, v105, v129
	v_exp_f32_e32 v101, v101
	v_mul_f32_e32 v100, 0x3fb8aa3b, v100
	v_sub_f32_e32 v103, v103, v66
	v_add_f32_e32 v129, v104, v129
	v_exp_f32_e32 v100, v100
	v_mul_f32_e32 v103, 0x3fb8aa3b, v103
	v_sub_f32_e32 v102, v102, v66
	v_sub_f32_e32 v97, v97, v66
	v_add_f32_e32 v129, v107, v129
	v_exp_f32_e32 v103, v103
	v_mul_f32_e32 v102, 0x3fb8aa3b, v102
	v_mul_f32_e32 v97, 0x3fb8aa3b, v97
	v_add_f32_e32 v129, v106, v129
	v_exp_f32_e32 v102, v102
	v_exp_f32_e32 v130, v97
	v_sub_f32_e32 v96, v96, v66
	v_sub_f32_e32 v97, v99, v66
	v_add_f32_e32 v129, v101, v129
	v_mul_f32_e32 v96, 0x3fb8aa3b, v96
	v_mul_f32_e32 v97, 0x3fb8aa3b, v97
	v_add_f32_e32 v129, v100, v129
	v_exp_f32_e32 v131, v96
	v_exp_f32_e32 v99, v97
	v_sub_f32_e32 v97, v98, v66
	v_sub_f32_e32 v93, v93, v66
	v_add_f32_e32 v96, v103, v129
	v_mul_f32_e32 v97, 0x3fb8aa3b, v97
	v_mul_f32_e32 v93, 0x3fb8aa3b, v93
	v_add_f32_e32 v96, v102, v96
	v_exp_f32_e32 v98, v97
	v_exp_f32_e32 v129, v93
	v_sub_f32_e32 v92, v92, v66
	v_sub_f32_e32 v93, v95, v66
	v_add_f32_e32 v96, v130, v96
	v_mul_f32_e32 v92, 0x3fb8aa3b, v92
	v_mul_f32_e32 v93, 0x3fb8aa3b, v93
	v_add_f32_e32 v96, v131, v96
	v_exp_f32_e32 v168, v92
	v_exp_f32_e32 v169, v93
	v_sub_f32_e32 v93, v94, v66
	v_sub_f32_e32 v89, v89, v66
	v_add_f32_e32 v92, v99, v96
	v_mul_f32_e32 v93, 0x3fb8aa3b, v93
	v_mul_f32_e32 v89, 0x3fb8aa3b, v89
	v_add_f32_e32 v92, v98, v92
	v_exp_f32_e32 v170, v93
	v_exp_f32_e32 v171, v89
	v_sub_f32_e32 v88, v88, v66
	v_sub_f32_e32 v89, v91, v66
	v_add_f32_e32 v92, v129, v92
	v_mul_f32_e32 v88, 0x3fb8aa3b, v88
	v_mul_f32_e32 v89, 0x3fb8aa3b, v89
	v_add_f32_e32 v92, v168, v92
	v_exp_f32_e32 v188, v88
	v_exp_f32_e32 v189, v89
	v_sub_f32_e32 v89, v90, v66
	v_sub_f32_e32 v85, v85, v66
	v_sub_f32_e32 v77, v77, v66
	v_add_f32_e32 v88, v169, v92
	v_mul_f32_e32 v89, 0x3fb8aa3b, v89
	v_mul_f32_e32 v85, 0x3fb8aa3b, v85
	v_mul_f32_e32 v77, 0x3fb8aa3b, v77
	v_add_f32_e32 v88, v170, v88
	v_exp_f32_e32 v190, v89
	v_exp_f32_e32 v191, v85
	v_sub_f32_e32 v84, v84, v66
	v_sub_f32_e32 v85, v87, v66
	v_exp_f32_e32 v195, v77
	v_sub_f32_e32 v77, v79, v66
	v_add_f32_e32 v88, v171, v88
	v_mul_f32_e32 v84, 0x3fb8aa3b, v84
	v_mul_f32_e32 v85, 0x3fb8aa3b, v85
	v_mul_f32_e32 v77, 0x3fb8aa3b, v77
	v_add_f32_e32 v88, v188, v88
	v_exp_f32_e32 v192, v84
	v_exp_f32_e32 v193, v85
	v_sub_f32_e32 v85, v86, v66
	v_exp_f32_e32 v197, v77
	v_sub_f32_e32 v77, v78, v66
	v_add_f32_e32 v84, v189, v88
	v_mul_f32_e32 v85, 0x3fb8aa3b, v85
	v_mul_f32_e32 v77, 0x3fb8aa3b, v77
	v_add_f32_e32 v84, v190, v84
	v_exp_f32_e32 v194, v85
	v_sub_f32_e32 v76, v76, v66
	v_exp_f32_e32 v198, v77
	v_sub_f32_e32 v77, v81, v66
	v_add_f32_e32 v84, v191, v84
	v_mul_f32_e32 v76, 0x3fb8aa3b, v76
	v_mul_f32_e32 v77, 0x3fb8aa3b, v77
	v_add_f32_e32 v84, v192, v84
	v_exp_f32_e32 v196, v76
	v_exp_f32_e32 v199, v77
	v_sub_f32_e32 v77, v80, v66
	v_add_f32_e32 v76, v193, v84
	v_mul_f32_e32 v77, 0x3fb8aa3b, v77
	v_add_f32_e32 v76, v194, v76
	v_exp_f32_e32 v200, v77
	v_sub_f32_e32 v77, v83, v66
	v_add_f32_e32 v76, v195, v76
	v_mul_f32_e32 v77, 0x3fb8aa3b, v77
	v_add_f32_e32 v76, v196, v76
	v_exp_f32_e32 v201, v77
	v_sub_f32_e32 v77, v82, v66
	v_sub_f32_e32 v73, v73, v66
	v_add_f32_e32 v76, v197, v76
	v_mul_f32_e32 v77, 0x3fb8aa3b, v77
	v_mul_f32_e32 v73, 0x3fb8aa3b, v73
	v_add_f32_e32 v76, v198, v76
	v_exp_f32_e32 v202, v77
	v_exp_f32_e32 v203, v73
	v_sub_f32_e32 v72, v72, v66
	v_sub_f32_e32 v73, v75, v66
	v_add_f32_e32 v76, v199, v76
	v_mul_f32_e32 v72, 0x3fb8aa3b, v72
	v_mul_f32_e32 v73, 0x3fb8aa3b, v73
	v_add_f32_e32 v76, v200, v76
	v_exp_f32_e32 v204, v72
	v_exp_f32_e32 v205, v73
	v_sub_f32_e32 v73, v74, v66
	v_sub_f32_e32 v69, v69, v66
	v_add_f32_e32 v72, v201, v76
	v_mul_f32_e32 v73, 0x3fb8aa3b, v73
	v_mul_f32_e32 v69, 0x3fb8aa3b, v69
	v_add_f32_e32 v72, v202, v72
	v_exp_f32_e32 v206, v73
	v_exp_f32_e32 v207, v69
	v_sub_f32_e32 v68, v68, v66
	v_sub_f32_e32 v69, v71, v66
	v_add_f32_e32 v72, v203, v72
	v_mul_f32_e32 v68, 0x3fb8aa3b, v68
	v_mul_f32_e32 v69, 0x3fb8aa3b, v69
	v_add_f32_e32 v72, v204, v72
	v_exp_f32_e32 v208, v68
	v_exp_f32_e32 v209, v69
	v_sub_f32_e32 v69, v70, v66
	v_add_f32_e32 v68, v205, v72
	v_mul_f32_e32 v69, 0x3fb8aa3b, v69
	v_sub_f32_e32 v65, v65, v66
	v_add_f32_e32 v68, v206, v68
	v_exp_f32_e32 v210, v69
	v_mul_f32_e32 v65, 0x3fb8aa3b, v65
	v_sub_f32_e32 v64, v64, v66
	v_add_f32_e32 v68, v207, v68
	v_exp_f32_e32 v211, v65
	v_mul_f32_e32 v64, 0x3fb8aa3b, v64
	v_add_f32_e32 v68, v208, v68
	v_exp_f32_e32 v212, v64
	v_add_f32_e32 v64, v209, v68
	v_add_f32_e32 v64, v210, v64
	v_add_f32_e32 v64, v211, v64
	v_add_f32_e32 v64, v212, v64
	ds_bpermute_b32 v65, v163, v64
	v_cvt_pk_bf16_f32 v92, v67, v128
	v_cvt_pk_bf16_f32 v93, v125, v124
	v_cvt_pk_bf16_f32 v94, v127, v126
	v_cvt_pk_bf16_f32 v95, v121, v120
	s_waitcnt lgkmcnt(0)
	v_add_f32_e32 v96, v64, v65
	ds_bpermute_b32 v97, v164, v96
	v_cvt_pk_bf16_f32 v88, v123, v122
	v_cvt_pk_bf16_f32 v89, v117, v116
	v_cvt_pk_bf16_f32 v90, v119, v118
	v_cvt_pk_bf16_f32 v91, v113, v112
	v_cvt_pk_bf16_f32 v84, v115, v114
	v_cvt_pk_bf16_f32 v85, v109, v108
	v_cvt_pk_bf16_f32 v86, v111, v110
	v_cvt_pk_bf16_f32 v87, v105, v104
	v_cvt_pk_bf16_f32 v80, v107, v106
	v_cvt_pk_bf16_f32 v81, v101, v100
	v_cvt_pk_bf16_f32 v82, v103, v102
	v_cvt_pk_bf16_f32 v83, v130, v131
	v_cvt_pk_bf16_f32 v76, v99, v98
	v_cvt_pk_bf16_f32 v77, v129, v168
	v_cvt_pk_bf16_f32 v78, v169, v170
	v_cvt_pk_bf16_f32 v79, v171, v188
	v_cvt_pk_bf16_f32 v72, v189, v190
	v_cvt_pk_bf16_f32 v73, v191, v192
	v_cvt_pk_bf16_f32 v74, v193, v194
	v_cvt_pk_bf16_f32 v75, v195, v196
	v_cvt_pk_bf16_f32 v68, v197, v198
	v_cvt_pk_bf16_f32 v69, v199, v200
	v_cvt_pk_bf16_f32 v70, v201, v202
	v_cvt_pk_bf16_f32 v71, v203, v204
	v_cvt_pk_bf16_f32 v64, v205, v206
	v_cvt_pk_bf16_f32 v65, v207, v208
	v_cvt_pk_bf16_f32 v66, v209, v210
	v_cvt_pk_bf16_f32 v67, v211, v212
	v_cndmask_b32_e64 v98, 0, 1, s[4:5]
	v_cmp_ne_u32_e64 s[44:45], 1, v98
	s_andn2_b64 vcc, exec, s[4:5]
	s_mov_b64 s[4:5], -1
	s_cbranch_vccnz .LBB0_635
	v_readlane_b32 s4, v250, 13
	s_add_i32 s6, s59, s4
	s_mov_b64 s[4:5], 0
